# v53: poll cadence - the 4-workgroup group barrier polls its counter back to back (no s_sleep between relaxed sc1 loads)
# baseline (speedup 1.0000x reference)
.Lgb_poll:
	global_load_dword v0, v1, s[6:7] sc1
	s_waitcnt vmcnt(0)
	v_cmp_le_u32_e32 vcc, s8, v0
	s_cbranch_vccnz .Lgb_acq
	s_add_i32 s9, s9, 1
	s_cmp_lt_u32 s9, 0x400000
	s_cbranch_scc1 .Lgb_poll
